# in-loop grid barrier rewritten: globally last XCC leader releases every XCC generation word directly (one hop less for 7 of 8 XCDs), barrier index from the phase counter instead of divisions
# speedup vs baseline: 1.0160x; 1.0160x over previous
.LBB0_605:
	s_waitcnt vmcnt(0)
	s_waitcnt vmcnt(0) lgkmcnt(0)
	s_barrier
	s_and_saveexec_b64 s[4:5], s[88:89]
	v_readlane_b32 s22, v249, 57
	v_readlane_b32 s24, v249, 59
	v_readlane_b32 s26, v249, 61
	v_readlane_b32 s28, v249, 63
	v_readlane_b32 s30, v248, 1
	v_readlane_b32 s34, v248, 3
	v_readlane_b32 s36, v248, 5
	v_readlane_b32 s23, v249, 58
	v_readlane_b32 s25, v249, 60
	v_readlane_b32 s27, v249, 62
	v_readlane_b32 s29, v248, 0
	v_readlane_b32 s31, v248, 2
	v_readlane_b32 s35, v248, 4
	v_readlane_b32 s37, v248, 6
	v_readlane_b32 s21, v248, 7
	s_cbranch_execz .LBB0_133
	buffer_inv sc1
	v_readlane_b32 s6, v249, 50
	v_readlane_b32 s7, v249, 51
	v_readlane_b32 s8, v249, 35
	v_readlane_b32 s9, v249, 36
	v_readlane_b32 s10, v249, 37
	v_readlane_b32 s11, v249, 38
	v_mov_b32_e32 v0, s6
	v_mov_b32_e32 v2, s7
	ds_read_b32 v3, v0
	ds_read_b32 v2, v2
	v_mov_b32_e32 v4, 1
	s_add_i32 s15, s3, 2
	s_nop 2
	global_atomic_add v4, v1, v4, s[8:9] sc0
	s_waitcnt vmcnt(0) lgkmcnt(0)
	v_max_u32_e32 v3, 1, v3
	v_max_u32_e32 v2, 1, v2
	v_readfirstlane_b32 s12, v4
	v_readfirstlane_b32 s13, v3
	v_readfirstlane_b32 s14, v2
	s_mul_i32 s16, s15, s13
	s_add_i32 s12, s12, 1
	s_cmp_lg_u32 s12, s16
	s_cbranch_scc1 .Lb_wait
	s_bitcmp1_b32 0xd5b56, s3
	s_cbranch_scc1 .Lb_nowb
	buffer_wbl2 sc1
.Lb_nowb:
	v_mov_b32_e32 v4, 1
	s_waitcnt vmcnt(0)
	global_atomic_add v4, v1, v4, s[10:11] sc0
	s_waitcnt vmcnt(0)
	v_readfirstlane_b32 s12, v4
	s_mul_i32 s16, s15, s14
	s_add_i32 s12, s12, 1
	s_cmp_lg_u32 s12, s16
	s_cbranch_scc1 .Lb_wait
	s_add_u32 s6, s22, 0x2200
	s_addc_u32 s7, s23, 0
	v_mov_b32_e32 v4, 1
	global_atomic_add v1, v4, s[6:7]
	global_atomic_add v1, v4, s[6:7] offset:256
	global_atomic_add v1, v4, s[6:7] offset:512
	global_atomic_add v1, v4, s[6:7] offset:768
	global_atomic_add v1, v4, s[6:7] offset:1024
	global_atomic_add v1, v4, s[6:7] offset:1280
	global_atomic_add v1, v4, s[6:7] offset:1536
	global_atomic_add v1, v4, s[6:7] offset:1792
	global_atomic_add v1, v4, s[6:7] offset:2048
	global_atomic_add v1, v4, s[6:7] offset:2304
	global_atomic_add v1, v4, s[6:7] offset:2560
	global_atomic_add v1, v4, s[6:7] offset:2816
	global_atomic_add v1, v4, s[6:7] offset:3072
	global_atomic_add v1, v4, s[6:7] offset:3328
	global_atomic_add v1, v4, s[6:7] offset:3584
	global_atomic_add v1, v4, s[6:7] offset:3840
	s_branch .Lb_done
.Lb_wait:
	s_add_i32 s16, s3, 1
	s_mov_b32 s12, 0
.Lb_spin:
	global_load_dword v4, v1, s[36:37] sc1
	s_waitcnt vmcnt(0)
	v_readfirstlane_b32 s13, v4
	s_cmp_lg_u32 s13, s16
	s_cbranch_scc1 .Lb_done
	s_sleep 1
	s_add_i32 s12, s12, 1
	s_cmp_lt_u32 s12, 0x800
	s_cbranch_scc1 .Lb_spin
